# P8 lora epilogue data path rewritten: in-place fused sigmoid chain (bias pre-scaled, (1+e)/sc as one fma), separate path for un-activated g tiles, per-row stores
# speedup vs baseline: 1.0045x; 1.0045x over previous
; __device__ __forceinline__ float sigm(float x) { return __builtin_amdgcn_rcpf(1.0f + __expf(-x)); }
;     __device__ __forceinline__ void operator()(const f32x4 (&acc)[2][2][4][2], const pg8::Unit& u, int wr, int wc, int fr, int fq) const {
;         const int reg = u.pn >> 2;
;         const int row0 = u.pm * 256 + wr * 64 + fr, cc0 = (u.pn & 3) * 256 + wc * 32 + 8 * fq;
;         f16_t* base = L + (size_t)reg * MT * RW + (size_t)row0 * RW + cc0;
;         const float* bp = bias + reg * RW + cc0;
;         const float sc = reg < 2 ? 0.6065306597126334f : 1.0f;
;         const bool act = reg < 4;
;         f32x4 bva[2][2];
; #pragma unroll
;         for (int bj = 0; bj < 2; ++bj)
; #pragma unroll
;             for (int n = 0; n < 2; ++n) bva[bj][n] = *(const f32x4*)(bp + bj * 128 + 4 * n);
; #pragma unroll
;         for (int bj = 0; bj < 2; ++bj)
; #pragma unroll
;             for (int n = 0; n < 2; ++n) {
;                 const f32x4 bv = bva[bj][n];
; #pragma unroll
;                 for (int ai = 0; ai < 2; ++ai)
; #pragma unroll
;                     for (int m = 0; m < 4; ++m) {
;                         f32x4 v = acc[ai][bj][m][n] + bv;
; #pragma unroll
;                         for (int j = 0; j < 4; ++j) { const float sg = sc * sigm(v[j]); v[j] = act ? sg : v[j]; }
;                         u32x2 w; w.x = pk_f16(v[0], v[1]); w.y = pk_f16(v[2], v[3]);
;                         *(u32x2*)(base + (size_t)(ai * 128 + m * 16) * RW + bj * 128 + 4 * n) = w;
;                     }
.LBB0_694:
	s_lshl_b32 s0, s33, 8
	s_ashr_i32 s15, s33, 2
	s_and_b32 s0, s0, 0x300
	v_or_b32_e32 v98, s0, v166
	s_lshl_b32 s0, s15, 10
	s_ashr_i32 s1, s0, 31
	s_lshl_b64 s[0:1], s[0:1], 2
	s_add_u32 s0, s62, s0
	s_addc_u32 s1, s63, s1
	v_lshlrev_b32_e32 v132, 2, v98
	global_load_dwordx4 v[140:143], v132, s[0:1]
	global_load_dwordx4 v[136:139], v132, s[0:1] offset:16
	v_lshl_add_u32 v96, s20, 8, v164
	s_mul_i32 s20, s15, 0x4400000
	v_ashrrev_i32_e32 v97, 31, v96
	s_cmp_lt_i32 s15, 2
	s_mul_hi_i32 s17, s15, 0x4400000
	v_lshlrev_b64 v[162:163], 11, v[96:97]
	v_lshlrev_b32_e32 v152, 1, v98
	global_load_dwordx4 v[96:99], v132, s[0:1] offset:528
	s_nop 0
	global_load_dwordx4 v[132:135], v132, s[0:1] offset:512
	s_cselect_b64 vcc, -1, 0
	s_add_u32 s0, s60, s20
	s_addc_u32 s1, s61, s17
	v_lshl_add_u64 v[162:163], s[0:1], 0, v[162:163]
	v_lshl_add_u64 v[162:163], v[162:163], 0, v[152:153]
	v_cndmask_b32_e32 v171, 1.0, v170, vcc
	s_cmp_lt_i32 s15, 4
	s_cselect_b64 vcc, -1, 0
	s_mov_b32 s33, s14
	s_mov_b32 s20, s16
	s_mov_b64 s[22:23], s[4:5]
	s_mov_b64 s[36:37], s[18:19]
	s_waitcnt vmcnt(0)
	s_cbranch_vccz .Lp8_noact
	v_rcp_f32_e32 v152, v171
	v_mov_b32_e32 v181, 0xbfb8aa3b
	v_mul_f32_e32 v140, 0xbfb8aa3b, v140
	v_mul_f32_e32 v141, 0xbfb8aa3b, v141
	v_mul_f32_e32 v142, 0xbfb8aa3b, v142
	v_mul_f32_e32 v143, 0xbfb8aa3b, v143
	v_mul_f32_e32 v136, 0xbfb8aa3b, v136
	v_mul_f32_e32 v137, 0xbfb8aa3b, v137
	v_mul_f32_e32 v138, 0xbfb8aa3b, v138
	v_mul_f32_e32 v139, 0xbfb8aa3b, v139
	v_mul_f32_e32 v132, 0xbfb8aa3b, v132
	v_mul_f32_e32 v133, 0xbfb8aa3b, v133
	v_mul_f32_e32 v134, 0xbfb8aa3b, v134
	v_mul_f32_e32 v135, 0xbfb8aa3b, v135
	v_mul_f32_e32 v96, 0xbfb8aa3b, v96
	v_mul_f32_e32 v97, 0xbfb8aa3b, v97
	v_mul_f32_e32 v98, 0xbfb8aa3b, v98
	v_mul_f32_e32 v99, 0xbfb8aa3b, v99
	v_fma_f32 v128, v128, v181, v140
	v_fma_f32 v129, v129, v181, v141
	v_fma_f32 v130, v130, v181, v142
	v_fma_f32 v131, v131, v181, v143
	v_fma_f32 v92, v92, v181, v136
	v_fma_f32 v93, v93, v181, v137
	v_fma_f32 v94, v94, v181, v138
	v_fma_f32 v95, v95, v181, v139
	v_exp_f32_e32 v128, v128
	v_exp_f32_e32 v129, v129
	v_exp_f32_e32 v130, v130
	v_exp_f32_e32 v131, v131
	v_exp_f32_e32 v92, v92
	v_exp_f32_e32 v93, v93
	v_exp_f32_e32 v94, v94
	v_exp_f32_e32 v95, v95
	v_fma_f32 v128, v128, v152, v152
	v_fma_f32 v129, v129, v152, v152
	v_fma_f32 v130, v130, v152, v152
	v_fma_f32 v131, v131, v152, v152
	v_fma_f32 v92, v92, v152, v152
	v_fma_f32 v93, v93, v152, v152
	v_fma_f32 v94, v94, v152, v152
	v_fma_f32 v95, v95, v152, v152
	v_rcp_f32_e32 v128, v128
	v_rcp_f32_e32 v129, v129
	v_rcp_f32_e32 v130, v130
	v_rcp_f32_e32 v131, v131
	v_rcp_f32_e32 v92, v92
	v_rcp_f32_e32 v93, v93
	v_rcp_f32_e32 v94, v94
	v_rcp_f32_e32 v95, v95
	v_cvt_pk_f16_f32 v128, v128, v129
	v_cvt_pk_f16_f32 v129, v130, v131
	v_cvt_pk_f16_f32 v130, v92, v93
	v_cvt_pk_f16_f32 v131, v94, v95
	global_store_dwordx4 v[162:163], v[128:131], off
	v_fma_f32 v60, v60, v181, v132
	v_fma_f32 v61, v61, v181, v133
	v_fma_f32 v62, v62, v181, v134
	v_fma_f32 v63, v63, v181, v135
	v_fma_f32 v28, v28, v181, v96
	v_fma_f32 v29, v29, v181, v97
	v_fma_f32 v30, v30, v181, v98
	v_fma_f32 v31, v31, v181, v99
	v_exp_f32_e32 v60, v60
	v_exp_f32_e32 v61, v61
	v_exp_f32_e32 v62, v62
	v_exp_f32_e32 v63, v63
	v_exp_f32_e32 v28, v28
	v_exp_f32_e32 v29, v29
	v_exp_f32_e32 v30, v30
	v_exp_f32_e32 v31, v31
	v_fma_f32 v60, v60, v152, v152
	v_fma_f32 v61, v61, v152, v152
	v_fma_f32 v62, v62, v152, v152
	v_fma_f32 v63, v63, v152, v152
	v_fma_f32 v28, v28, v152, v152
	v_fma_f32 v29, v29, v152, v152
	v_fma_f32 v30, v30, v152, v152
	v_fma_f32 v31, v31, v152, v152
	v_rcp_f32_e32 v60, v60
	v_rcp_f32_e32 v61, v61
	v_rcp_f32_e32 v62, v62
	v_rcp_f32_e32 v63, v63
	v_rcp_f32_e32 v28, v28
	v_rcp_f32_e32 v29, v29
	v_rcp_f32_e32 v30, v30
	v_rcp_f32_e32 v31, v31
	v_cvt_pk_f16_f32 v60, v60, v61
	v_cvt_pk_f16_f32 v61, v62, v63
	v_cvt_pk_f16_f32 v62, v28, v29
	v_cvt_pk_f16_f32 v63, v30, v31
	global_store_dwordx4 v[162:163], v[60:63], off offset:256
	v_add_co_u32_e64 v172, s[0:1], s71, v162
	v_addc_co_u32_e64 v173, s[0:1], 0, v163, s[0:1]
	v_fma_f32 v124, v124, v181, v140
	v_fma_f32 v125, v125, v181, v141
	v_fma_f32 v126, v126, v181, v142
	v_fma_f32 v127, v127, v181, v143
	v_fma_f32 v88, v88, v181, v136
	v_fma_f32 v89, v89, v181, v137
	v_fma_f32 v90, v90, v181, v138
	v_fma_f32 v91, v91, v181, v139
	v_exp_f32_e32 v124, v124
	v_exp_f32_e32 v125, v125
	v_exp_f32_e32 v126, v126
	v_exp_f32_e32 v127, v127
	v_exp_f32_e32 v88, v88
	v_exp_f32_e32 v89, v89
	v_exp_f32_e32 v90, v90
	v_exp_f32_e32 v91, v91
	v_fma_f32 v124, v124, v152, v152
	v_fma_f32 v125, v125, v152, v152
	v_fma_f32 v126, v126, v152, v152
	v_fma_f32 v127, v127, v152, v152
	v_fma_f32 v88, v88, v152, v152
	v_fma_f32 v89, v89, v152, v152
	v_fma_f32 v90, v90, v152, v152
	v_fma_f32 v91, v91, v152, v152
	v_rcp_f32_e32 v124, v124
	v_rcp_f32_e32 v125, v125
	v_rcp_f32_e32 v126, v126
	v_rcp_f32_e32 v127, v127
	v_rcp_f32_e32 v88, v88
	v_rcp_f32_e32 v89, v89
	v_rcp_f32_e32 v90, v90
	v_rcp_f32_e32 v91, v91
	v_cvt_pk_f16_f32 v124, v124, v125
	v_cvt_pk_f16_f32 v125, v126, v127
	v_cvt_pk_f16_f32 v126, v88, v89
	v_cvt_pk_f16_f32 v127, v90, v91
	global_store_dwordx4 v[172:173], v[124:127], off
	v_fma_f32 v56, v56, v181, v132
	v_fma_f32 v57, v57, v181, v133
	v_fma_f32 v58, v58, v181, v134
	v_fma_f32 v59, v59, v181, v135
	v_fma_f32 v24, v24, v181, v96
	v_fma_f32 v25, v25, v181, v97
	v_fma_f32 v26, v26, v181, v98
	v_fma_f32 v27, v27, v181, v99
	v_exp_f32_e32 v56, v56
	v_exp_f32_e32 v57, v57
	v_exp_f32_e32 v58, v58
	v_exp_f32_e32 v59, v59
	v_exp_f32_e32 v24, v24
	v_exp_f32_e32 v25, v25
	v_exp_f32_e32 v26, v26
	v_exp_f32_e32 v27, v27
; __device__ __forceinline__ float sigm(float x) { return __builtin_amdgcn_rcpf(1.0f + __expf(-x)); }
;     __device__ __forceinline__ void operator()(const f32x4 (&acc)[2][2][4][2], const pg8::Unit& u, int wr, int wc, int fr, int fq) const {
;     ...
;                 for (int ai = 0; ai < 2; ++ai)
; #pragma unroll
;                     for (int m = 0; m < 4; ++m) {
;                         f32x4 v = acc[ai][bj][m][n] + bv;
; #pragma unroll
;                         for (int j = 0; j < 4; ++j) { const float sg = sc * sigm(v[j]); v[j] = act ? sg : v[j]; }
;                         u32x2 w; w.x = pk_f16(v[0], v[1]); w.y = pk_f16(v[2], v[3]);
;                         *(u32x2*)(base + (size_t)(ai * 128 + m * 16) * RW + bj * 128 + 4 * n) = w;
;                     }
	v_fma_f32 v56, v56, v152, v152
	v_fma_f32 v57, v57, v152, v152
	v_fma_f32 v58, v58, v152, v152
	v_fma_f32 v59, v59, v152, v152
	v_fma_f32 v24, v24, v152, v152
	v_fma_f32 v25, v25, v152, v152
	v_fma_f32 v26, v26, v152, v152
	v_fma_f32 v27, v27, v152, v152
	v_rcp_f32_e32 v56, v56
	v_rcp_f32_e32 v57, v57
	v_rcp_f32_e32 v58, v58
	v_rcp_f32_e32 v59, v59
	v_rcp_f32_e32 v24, v24
	v_rcp_f32_e32 v25, v25
	v_rcp_f32_e32 v26, v26
	v_rcp_f32_e32 v27, v27
	v_cvt_pk_f16_f32 v56, v56, v57
	v_cvt_pk_f16_f32 v57, v58, v59
	v_cvt_pk_f16_f32 v58, v24, v25
	v_cvt_pk_f16_f32 v59, v26, v27
	global_store_dwordx4 v[172:173], v[56:59], off offset:256
	s_mov_b32 s0, 0x10000
	v_add_co_u32_e64 v174, s[0:1], s0, v162
	v_addc_co_u32_e64 v175, s[0:1], 0, v163, s[0:1]
	v_fma_f32 v120, v120, v181, v140
	v_fma_f32 v121, v121, v181, v141
	v_fma_f32 v122, v122, v181, v142
	v_fma_f32 v123, v123, v181, v143
	v_fma_f32 v84, v84, v181, v136
	v_fma_f32 v85, v85, v181, v137
	v_fma_f32 v86, v86, v181, v138
	v_fma_f32 v87, v87, v181, v139
	v_exp_f32_e32 v120, v120
	v_exp_f32_e32 v121, v121
	v_exp_f32_e32 v122, v122
	v_exp_f32_e32 v123, v123
	v_exp_f32_e32 v84, v84
	v_exp_f32_e32 v85, v85
	v_exp_f32_e32 v86, v86
	v_exp_f32_e32 v87, v87
	v_fma_f32 v120, v120, v152, v152
	v_fma_f32 v121, v121, v152, v152
	v_fma_f32 v122, v122, v152, v152
	v_fma_f32 v123, v123, v152, v152
	v_fma_f32 v84, v84, v152, v152
	v_fma_f32 v85, v85, v152, v152
	v_fma_f32 v86, v86, v152, v152
	v_fma_f32 v87, v87, v152, v152
	v_rcp_f32_e32 v120, v120
	v_rcp_f32_e32 v121, v121
	v_rcp_f32_e32 v122, v122
	v_rcp_f32_e32 v123, v123
	v_rcp_f32_e32 v84, v84
	v_rcp_f32_e32 v85, v85
	v_rcp_f32_e32 v86, v86
	v_rcp_f32_e32 v87, v87
	v_cvt_pk_f16_f32 v120, v120, v121
	v_cvt_pk_f16_f32 v121, v122, v123
	v_cvt_pk_f16_f32 v122, v84, v85
	v_cvt_pk_f16_f32 v123, v86, v87
	global_store_dwordx4 v[174:175], v[120:123], off
	v_fma_f32 v52, v52, v181, v132
	v_fma_f32 v53, v53, v181, v133
	v_fma_f32 v54, v54, v181, v134
	v_fma_f32 v55, v55, v181, v135
	v_fma_f32 v20, v20, v181, v96
	v_fma_f32 v21, v21, v181, v97
	v_fma_f32 v22, v22, v181, v98
	v_fma_f32 v23, v23, v181, v99
	v_exp_f32_e32 v52, v52
	v_exp_f32_e32 v53, v53
	v_exp_f32_e32 v54, v54
	v_exp_f32_e32 v55, v55
	v_exp_f32_e32 v20, v20
	v_exp_f32_e32 v21, v21
	v_exp_f32_e32 v22, v22
	v_exp_f32_e32 v23, v23
	v_fma_f32 v52, v52, v152, v152
	v_fma_f32 v53, v53, v152, v152
	v_fma_f32 v54, v54, v152, v152
	v_fma_f32 v55, v55, v152, v152
	v_fma_f32 v20, v20, v152, v152
	v_fma_f32 v21, v21, v152, v152
	v_fma_f32 v22, v22, v152, v152
	v_fma_f32 v23, v23, v152, v152
	v_rcp_f32_e32 v52, v52
	v_rcp_f32_e32 v53, v53
	v_rcp_f32_e32 v54, v54
	v_rcp_f32_e32 v55, v55
	v_rcp_f32_e32 v20, v20
	v_rcp_f32_e32 v21, v21
	v_rcp_f32_e32 v22, v22
	v_rcp_f32_e32 v23, v23
	v_cvt_pk_f16_f32 v52, v52, v53
	v_cvt_pk_f16_f32 v53, v54, v55
	v_cvt_pk_f16_f32 v54, v20, v21
	v_cvt_pk_f16_f32 v55, v22, v23
	global_store_dwordx4 v[174:175], v[52:55], off offset:256
	s_mov_b32 s0, 0x18000
	v_add_co_u32_e64 v172, s[0:1], s0, v162
	v_addc_co_u32_e64 v173, s[0:1], 0, v163, s[0:1]
	v_fma_f32 v116, v116, v181, v140
	v_fma_f32 v117, v117, v181, v141
	v_fma_f32 v118, v118, v181, v142
	v_fma_f32 v119, v119, v181, v143
	v_fma_f32 v80, v80, v181, v136
	v_fma_f32 v81, v81, v181, v137
	v_fma_f32 v82, v82, v181, v138
	v_fma_f32 v83, v83, v181, v139
	v_exp_f32_e32 v116, v116
	v_exp_f32_e32 v117, v117
	v_exp_f32_e32 v118, v118
	v_exp_f32_e32 v119, v119
	v_exp_f32_e32 v80, v80
	v_exp_f32_e32 v81, v81
	v_exp_f32_e32 v82, v82
	v_exp_f32_e32 v83, v83
	v_fma_f32 v116, v116, v152, v152
	v_fma_f32 v117, v117, v152, v152
	v_fma_f32 v118, v118, v152, v152
	v_fma_f32 v119, v119, v152, v152
	v_fma_f32 v80, v80, v152, v152
	v_fma_f32 v81, v81, v152, v152
	v_fma_f32 v82, v82, v152, v152
	v_fma_f32 v83, v83, v152, v152
	v_rcp_f32_e32 v116, v116
	v_rcp_f32_e32 v117, v117
	v_rcp_f32_e32 v118, v118
	v_rcp_f32_e32 v119, v119
	v_rcp_f32_e32 v80, v80
	v_rcp_f32_e32 v81, v81
	v_rcp_f32_e32 v82, v82
	v_rcp_f32_e32 v83, v83
	v_cvt_pk_f16_f32 v116, v116, v117
	v_cvt_pk_f16_f32 v117, v118, v119
	v_cvt_pk_f16_f32 v118, v80, v81
	v_cvt_pk_f16_f32 v119, v82, v83
	global_store_dwordx4 v[172:173], v[116:119], off
	v_fma_f32 v48, v48, v181, v132
	v_fma_f32 v49, v49, v181, v133
	v_fma_f32 v50, v50, v181, v134
	v_fma_f32 v51, v51, v181, v135
	v_fma_f32 v16, v16, v181, v96
	v_fma_f32 v17, v17, v181, v97
	v_fma_f32 v18, v18, v181, v98
	v_fma_f32 v19, v19, v181, v99
	v_exp_f32_e32 v48, v48
	v_exp_f32_e32 v49, v49
	v_exp_f32_e32 v50, v50
	v_exp_f32_e32 v51, v51
	v_exp_f32_e32 v16, v16
	v_exp_f32_e32 v17, v17
	v_exp_f32_e32 v18, v18
	v_exp_f32_e32 v19, v19
	v_fma_f32 v48, v48, v152, v152
	v_fma_f32 v49, v49, v152, v152
	v_fma_f32 v50, v50, v152, v152
	v_fma_f32 v51, v51, v152, v152
	v_fma_f32 v16, v16, v152, v152
	v_fma_f32 v17, v17, v152, v152
	v_fma_f32 v18, v18, v152, v152
	v_fma_f32 v19, v19, v152, v152
	v_rcp_f32_e32 v48, v48
	v_rcp_f32_e32 v49, v49
	v_rcp_f32_e32 v50, v50
	v_rcp_f32_e32 v51, v51
	v_rcp_f32_e32 v16, v16
	v_rcp_f32_e32 v17, v17
	v_rcp_f32_e32 v18, v18
	v_rcp_f32_e32 v19, v19
	v_cvt_pk_f16_f32 v48, v48, v49
	v_cvt_pk_f16_f32 v49, v50, v51
	v_cvt_pk_f16_f32 v50, v16, v17
	v_cvt_pk_f16_f32 v51, v18, v19
	global_store_dwordx4 v[172:173], v[48:51], off offset:256
	v_add_co_u32_e64 v174, s[0:1], s85, v162
	v_addc_co_u32_e64 v175, s[0:1], 0, v163, s[0:1]
	v_fma_f32 v112, v112, v181, v140
	v_fma_f32 v113, v113, v181, v141
	v_fma_f32 v114, v114, v181, v142
	v_fma_f32 v115, v115, v181, v143
	v_fma_f32 v76, v76, v181, v136
	v_fma_f32 v77, v77, v181, v137
	v_fma_f32 v78, v78, v181, v138
	v_fma_f32 v79, v79, v181, v139
	v_exp_f32_e32 v112, v112
; __device__ __forceinline__ float sigm(float x) { return __builtin_amdgcn_rcpf(1.0f + __expf(-x)); }
;     __device__ __forceinline__ void operator()(const f32x4 (&acc)[2][2][4][2], const pg8::Unit& u, int wr, int wc, int fr, int fq) const {
;     ...
;                 for (int ai = 0; ai < 2; ++ai)
; #pragma unroll
;                     for (int m = 0; m < 4; ++m) {
;                         f32x4 v = acc[ai][bj][m][n] + bv;
; #pragma unroll
;                         for (int j = 0; j < 4; ++j) { const float sg = sc * sigm(v[j]); v[j] = act ? sg : v[j]; }
;                         u32x2 w; w.x = pk_f16(v[0], v[1]); w.y = pk_f16(v[2], v[3]);
;                         *(u32x2*)(base + (size_t)(ai * 128 + m * 16) * RW + bj * 128 + 4 * n) = w;
;                     }
	v_exp_f32_e32 v113, v113
	v_exp_f32_e32 v114, v114
	v_exp_f32_e32 v115, v115
	v_exp_f32_e32 v76, v76
	v_exp_f32_e32 v77, v77
	v_exp_f32_e32 v78, v78
	v_exp_f32_e32 v79, v79
	v_fma_f32 v112, v112, v152, v152
	v_fma_f32 v113, v113, v152, v152
	v_fma_f32 v114, v114, v152, v152
	v_fma_f32 v115, v115, v152, v152
	v_fma_f32 v76, v76, v152, v152
	v_fma_f32 v77, v77, v152, v152
	v_fma_f32 v78, v78, v152, v152
	v_fma_f32 v79, v79, v152, v152
	v_rcp_f32_e32 v112, v112
	v_rcp_f32_e32 v113, v113
	v_rcp_f32_e32 v114, v114
	v_rcp_f32_e32 v115, v115
	v_rcp_f32_e32 v76, v76
	v_rcp_f32_e32 v77, v77
	v_rcp_f32_e32 v78, v78
	v_rcp_f32_e32 v79, v79
	v_cvt_pk_f16_f32 v112, v112, v113
	v_cvt_pk_f16_f32 v113, v114, v115
	v_cvt_pk_f16_f32 v114, v76, v77
	v_cvt_pk_f16_f32 v115, v78, v79
	global_store_dwordx4 v[174:175], v[112:115], off
	v_fma_f32 v44, v44, v181, v132
	v_fma_f32 v45, v45, v181, v133
	v_fma_f32 v46, v46, v181, v134
	v_fma_f32 v47, v47, v181, v135
	v_fma_f32 v12, v12, v181, v96
	v_fma_f32 v13, v13, v181, v97
	v_fma_f32 v14, v14, v181, v98
	v_fma_f32 v15, v15, v181, v99
	v_exp_f32_e32 v44, v44
	v_exp_f32_e32 v45, v45
	v_exp_f32_e32 v46, v46
	v_exp_f32_e32 v47, v47
	v_exp_f32_e32 v12, v12
	v_exp_f32_e32 v13, v13
	v_exp_f32_e32 v14, v14
	v_exp_f32_e32 v15, v15
	v_fma_f32 v44, v44, v152, v152
	v_fma_f32 v45, v45, v152, v152
	v_fma_f32 v46, v46, v152, v152
	v_fma_f32 v47, v47, v152, v152
	v_fma_f32 v12, v12, v152, v152
	v_fma_f32 v13, v13, v152, v152
	v_fma_f32 v14, v14, v152, v152
	v_fma_f32 v15, v15, v152, v152
	v_rcp_f32_e32 v44, v44
	v_rcp_f32_e32 v45, v45
	v_rcp_f32_e32 v46, v46
	v_rcp_f32_e32 v47, v47
	v_rcp_f32_e32 v12, v12
	v_rcp_f32_e32 v13, v13
	v_rcp_f32_e32 v14, v14
	v_rcp_f32_e32 v15, v15
	v_cvt_pk_f16_f32 v44, v44, v45
	v_cvt_pk_f16_f32 v45, v46, v47
	v_cvt_pk_f16_f32 v46, v12, v13
	v_cvt_pk_f16_f32 v47, v14, v15
	global_store_dwordx4 v[174:175], v[44:47], off offset:256
	v_add_co_u32_e64 v172, s[0:1], s94, v162
	v_addc_co_u32_e64 v173, s[0:1], 0, v163, s[0:1]
	v_fma_f32 v108, v108, v181, v140
	v_fma_f32 v109, v109, v181, v141
	v_fma_f32 v110, v110, v181, v142
	v_fma_f32 v111, v111, v181, v143
	v_fma_f32 v72, v72, v181, v136
	v_fma_f32 v73, v73, v181, v137
	v_fma_f32 v74, v74, v181, v138
	v_fma_f32 v75, v75, v181, v139
	v_exp_f32_e32 v108, v108
	v_exp_f32_e32 v109, v109
	v_exp_f32_e32 v110, v110
	v_exp_f32_e32 v111, v111
	v_exp_f32_e32 v72, v72
	v_exp_f32_e32 v73, v73
	v_exp_f32_e32 v74, v74
	v_exp_f32_e32 v75, v75
	v_fma_f32 v108, v108, v152, v152
	v_fma_f32 v109, v109, v152, v152
	v_fma_f32 v110, v110, v152, v152
	v_fma_f32 v111, v111, v152, v152
	v_fma_f32 v72, v72, v152, v152
	v_fma_f32 v73, v73, v152, v152
	v_fma_f32 v74, v74, v152, v152
	v_fma_f32 v75, v75, v152, v152
	v_rcp_f32_e32 v108, v108
	v_rcp_f32_e32 v109, v109
	v_rcp_f32_e32 v110, v110
	v_rcp_f32_e32 v111, v111
	v_rcp_f32_e32 v72, v72
	v_rcp_f32_e32 v73, v73
	v_rcp_f32_e32 v74, v74
	v_rcp_f32_e32 v75, v75
	v_cvt_pk_f16_f32 v108, v108, v109
	v_cvt_pk_f16_f32 v109, v110, v111
	v_cvt_pk_f16_f32 v110, v72, v73
	v_cvt_pk_f16_f32 v111, v74, v75
	global_store_dwordx4 v[172:173], v[108:111], off
	v_fma_f32 v40, v40, v181, v132
	v_fma_f32 v41, v41, v181, v133
	v_fma_f32 v42, v42, v181, v134
	v_fma_f32 v43, v43, v181, v135
	v_fma_f32 v8, v8, v181, v96
	v_fma_f32 v9, v9, v181, v97
	v_fma_f32 v10, v10, v181, v98
	v_fma_f32 v11, v11, v181, v99
	v_exp_f32_e32 v40, v40
	v_exp_f32_e32 v41, v41
	v_exp_f32_e32 v42, v42
	v_exp_f32_e32 v43, v43
	v_exp_f32_e32 v8, v8
	v_exp_f32_e32 v9, v9
	v_exp_f32_e32 v10, v10
	v_exp_f32_e32 v11, v11
	v_fma_f32 v40, v40, v152, v152
	v_fma_f32 v41, v41, v152, v152
	v_fma_f32 v42, v42, v152, v152
	v_fma_f32 v43, v43, v152, v152
	v_fma_f32 v8, v8, v152, v152
	v_fma_f32 v9, v9, v152, v152
	v_fma_f32 v10, v10, v152, v152
	v_fma_f32 v11, v11, v152, v152
	v_rcp_f32_e32 v40, v40
	v_rcp_f32_e32 v41, v41
	v_rcp_f32_e32 v42, v42
	v_rcp_f32_e32 v43, v43
	v_rcp_f32_e32 v8, v8
	v_rcp_f32_e32 v9, v9
	v_rcp_f32_e32 v10, v10
	v_rcp_f32_e32 v11, v11
	v_cvt_pk_f16_f32 v40, v40, v41
	v_cvt_pk_f16_f32 v41, v42, v43
	v_cvt_pk_f16_f32 v42, v8, v9
	v_cvt_pk_f16_f32 v43, v10, v11
	global_store_dwordx4 v[172:173], v[40:43], off offset:256
	v_add_co_u32_e64 v174, s[0:1], s95, v162
	v_addc_co_u32_e64 v175, s[0:1], 0, v163, s[0:1]
	v_fma_f32 v104, v104, v181, v140
	v_fma_f32 v105, v105, v181, v141
	v_fma_f32 v106, v106, v181, v142
	v_fma_f32 v107, v107, v181, v143
	v_fma_f32 v68, v68, v181, v136
	v_fma_f32 v69, v69, v181, v137
	v_fma_f32 v70, v70, v181, v138
	v_fma_f32 v71, v71, v181, v139
	v_exp_f32_e32 v104, v104
	v_exp_f32_e32 v105, v105
	v_exp_f32_e32 v106, v106
	v_exp_f32_e32 v107, v107
	v_exp_f32_e32 v68, v68
	v_exp_f32_e32 v69, v69
	v_exp_f32_e32 v70, v70
	v_exp_f32_e32 v71, v71
	v_fma_f32 v104, v104, v152, v152
	v_fma_f32 v105, v105, v152, v152
	v_fma_f32 v106, v106, v152, v152
	v_fma_f32 v107, v107, v152, v152
	v_fma_f32 v68, v68, v152, v152
	v_fma_f32 v69, v69, v152, v152
	v_fma_f32 v70, v70, v152, v152
	v_fma_f32 v71, v71, v152, v152
	v_rcp_f32_e32 v104, v104
	v_rcp_f32_e32 v105, v105
	v_rcp_f32_e32 v106, v106
	v_rcp_f32_e32 v107, v107
	v_rcp_f32_e32 v68, v68
	v_rcp_f32_e32 v69, v69
	v_rcp_f32_e32 v70, v70
	v_rcp_f32_e32 v71, v71
	v_cvt_pk_f16_f32 v104, v104, v105
	v_cvt_pk_f16_f32 v105, v106, v107
	v_cvt_pk_f16_f32 v106, v68, v69
	v_cvt_pk_f16_f32 v107, v70, v71
	global_store_dwordx4 v[174:175], v[104:107], off
	v_fma_f32 v36, v36, v181, v132
	v_fma_f32 v37, v37, v181, v133
	v_fma_f32 v38, v38, v181, v134
	v_fma_f32 v39, v39, v181, v135
	v_fma_f32 v4, v4, v181, v96
	v_fma_f32 v5, v5, v181, v97
	v_fma_f32 v6, v6, v181, v98
	v_fma_f32 v7, v7, v181, v99
	v_exp_f32_e32 v36, v36
; __device__ __forceinline__ float sigm(float x) { return __builtin_amdgcn_rcpf(1.0f + __expf(-x)); }
;     __device__ __forceinline__ void operator()(const f32x4 (&acc)[2][2][4][2], const pg8::Unit& u, int wr, int wc, int fr, int fq) const {
;     ...
;                 for (int ai = 0; ai < 2; ++ai)
; #pragma unroll
;                     for (int m = 0; m < 4; ++m) {
;                         f32x4 v = acc[ai][bj][m][n] + bv;
; #pragma unroll
;                         for (int j = 0; j < 4; ++j) { const float sg = sc * sigm(v[j]); v[j] = act ? sg : v[j]; }
;                         u32x2 w; w.x = pk_f16(v[0], v[1]); w.y = pk_f16(v[2], v[3]);
;                         *(u32x2*)(base + (size_t)(ai * 128 + m * 16) * RW + bj * 128 + 4 * n) = w;
;                     }
	v_exp_f32_e32 v37, v37
	v_exp_f32_e32 v38, v38
	v_exp_f32_e32 v39, v39
	v_exp_f32_e32 v4, v4
	v_exp_f32_e32 v5, v5
	v_exp_f32_e32 v6, v6
	v_exp_f32_e32 v7, v7
	v_fma_f32 v36, v36, v152, v152
	v_fma_f32 v37, v37, v152, v152
	v_fma_f32 v38, v38, v152, v152
	v_fma_f32 v39, v39, v152, v152
	v_fma_f32 v4, v4, v152, v152
	v_fma_f32 v5, v5, v152, v152
	v_fma_f32 v6, v6, v152, v152
	v_fma_f32 v7, v7, v152, v152
	v_rcp_f32_e32 v36, v36
	v_rcp_f32_e32 v37, v37
	v_rcp_f32_e32 v38, v38
	v_rcp_f32_e32 v39, v39
	v_rcp_f32_e32 v4, v4
	v_rcp_f32_e32 v5, v5
	v_rcp_f32_e32 v6, v6
	v_rcp_f32_e32 v7, v7
	v_cvt_pk_f16_f32 v36, v36, v37
	v_cvt_pk_f16_f32 v37, v38, v39
	v_cvt_pk_f16_f32 v38, v4, v5
	v_cvt_pk_f16_f32 v39, v6, v7
	global_store_dwordx4 v[174:175], v[36:39], off offset:256
	v_add_co_u32_e64 v172, s[0:1], s96, v162
	v_addc_co_u32_e64 v173, s[0:1], 0, v163, s[0:1]
	v_fma_f32 v100, v100, v181, v140
	v_fma_f32 v101, v101, v181, v141
	v_fma_f32 v102, v102, v181, v142
	v_fma_f32 v103, v103, v181, v143
	v_fma_f32 v64, v64, v181, v136
	v_fma_f32 v65, v65, v181, v137
	v_fma_f32 v66, v66, v181, v138
	v_fma_f32 v67, v67, v181, v139
	v_exp_f32_e32 v100, v100
	v_exp_f32_e32 v101, v101
	v_exp_f32_e32 v102, v102
	v_exp_f32_e32 v103, v103
	v_exp_f32_e32 v64, v64
	v_exp_f32_e32 v65, v65
	v_exp_f32_e32 v66, v66
	v_exp_f32_e32 v67, v67
	v_fma_f32 v100, v100, v152, v152
	v_fma_f32 v101, v101, v152, v152
	v_fma_f32 v102, v102, v152, v152
	v_fma_f32 v103, v103, v152, v152
	v_fma_f32 v64, v64, v152, v152
	v_fma_f32 v65, v65, v152, v152
	v_fma_f32 v66, v66, v152, v152
	v_fma_f32 v67, v67, v152, v152
	v_rcp_f32_e32 v100, v100
	v_rcp_f32_e32 v101, v101
	v_rcp_f32_e32 v102, v102
	v_rcp_f32_e32 v103, v103
	v_rcp_f32_e32 v64, v64
	v_rcp_f32_e32 v65, v65
	v_rcp_f32_e32 v66, v66
	v_rcp_f32_e32 v67, v67
	v_cvt_pk_f16_f32 v100, v100, v101
	v_cvt_pk_f16_f32 v101, v102, v103
	v_cvt_pk_f16_f32 v102, v64, v65
	v_cvt_pk_f16_f32 v103, v66, v67
	global_store_dwordx4 v[172:173], v[100:103], off
	v_fma_f32 v32, v32, v181, v132
	v_fma_f32 v33, v33, v181, v133
	v_fma_f32 v34, v34, v181, v134
	v_fma_f32 v35, v35, v181, v135
	v_fma_f32 v0, v0, v181, v96
	v_fma_f32 v1, v1, v181, v97
	v_fma_f32 v2, v2, v181, v98
	v_fma_f32 v3, v3, v181, v99
	v_exp_f32_e32 v32, v32
	v_exp_f32_e32 v33, v33
	v_exp_f32_e32 v34, v34
	v_exp_f32_e32 v35, v35
	v_exp_f32_e32 v0, v0
	v_exp_f32_e32 v1, v1
	v_exp_f32_e32 v2, v2
	v_exp_f32_e32 v3, v3
	v_fma_f32 v32, v32, v152, v152
	v_fma_f32 v33, v33, v152, v152
	v_fma_f32 v34, v34, v152, v152
	v_fma_f32 v35, v35, v152, v152
	v_fma_f32 v0, v0, v152, v152
	v_fma_f32 v1, v1, v152, v152
	v_fma_f32 v2, v2, v152, v152
	v_fma_f32 v3, v3, v152, v152
	v_rcp_f32_e32 v32, v32
	v_rcp_f32_e32 v33, v33
	v_rcp_f32_e32 v34, v34
	v_rcp_f32_e32 v35, v35
	v_rcp_f32_e32 v0, v0
	v_rcp_f32_e32 v1, v1
	v_rcp_f32_e32 v2, v2
	v_rcp_f32_e32 v3, v3
	v_cvt_pk_f16_f32 v32, v32, v33
	v_cvt_pk_f16_f32 v33, v34, v35
	v_cvt_pk_f16_f32 v34, v0, v1
	v_cvt_pk_f16_f32 v35, v2, v3
	global_store_dwordx4 v[172:173], v[32:35], off offset:256
	s_branch .Lp8_epi_done
.Lp8_noact:
	v_add_f32_e32 v128, v128, v140
	v_add_f32_e32 v129, v129, v141
	v_add_f32_e32 v130, v130, v142
	v_add_f32_e32 v131, v131, v143
	v_add_f32_e32 v92, v92, v136
	v_add_f32_e32 v93, v93, v137
	v_add_f32_e32 v94, v94, v138
	v_add_f32_e32 v95, v95, v139
	v_cvt_pk_f16_f32 v128, v128, v129
	v_cvt_pk_f16_f32 v129, v130, v131
	v_cvt_pk_f16_f32 v130, v92, v93
	v_cvt_pk_f16_f32 v131, v94, v95
	global_store_dwordx4 v[162:163], v[128:131], off
	v_add_f32_e32 v60, v60, v132
	v_add_f32_e32 v61, v61, v133
	v_add_f32_e32 v62, v62, v134
	v_add_f32_e32 v63, v63, v135
	v_add_f32_e32 v28, v28, v96
	v_add_f32_e32 v29, v29, v97
	v_add_f32_e32 v30, v30, v98
	v_add_f32_e32 v31, v31, v99
	v_cvt_pk_f16_f32 v60, v60, v61
	v_cvt_pk_f16_f32 v61, v62, v63
	v_cvt_pk_f16_f32 v62, v28, v29
	v_cvt_pk_f16_f32 v63, v30, v31
	global_store_dwordx4 v[162:163], v[60:63], off offset:256
	v_add_co_u32_e64 v172, s[0:1], s71, v162
	v_addc_co_u32_e64 v173, s[0:1], 0, v163, s[0:1]
	v_add_f32_e32 v124, v124, v140
	v_add_f32_e32 v125, v125, v141
	v_add_f32_e32 v126, v126, v142
	v_add_f32_e32 v127, v127, v143
	v_add_f32_e32 v88, v88, v136
	v_add_f32_e32 v89, v89, v137
	v_add_f32_e32 v90, v90, v138
	v_add_f32_e32 v91, v91, v139
	v_cvt_pk_f16_f32 v124, v124, v125
	v_cvt_pk_f16_f32 v125, v126, v127
	v_cvt_pk_f16_f32 v126, v88, v89
	v_cvt_pk_f16_f32 v127, v90, v91
	global_store_dwordx4 v[172:173], v[124:127], off
	v_add_f32_e32 v56, v56, v132
	v_add_f32_e32 v57, v57, v133
	v_add_f32_e32 v58, v58, v134
	v_add_f32_e32 v59, v59, v135
	v_add_f32_e32 v24, v24, v96
	v_add_f32_e32 v25, v25, v97
	v_add_f32_e32 v26, v26, v98
	v_add_f32_e32 v27, v27, v99
	v_cvt_pk_f16_f32 v56, v56, v57
	v_cvt_pk_f16_f32 v57, v58, v59
	v_cvt_pk_f16_f32 v58, v24, v25
	v_cvt_pk_f16_f32 v59, v26, v27
	global_store_dwordx4 v[172:173], v[56:59], off offset:256
	s_mov_b32 s0, 0x10000
	v_add_co_u32_e64 v174, s[0:1], s0, v162
	v_addc_co_u32_e64 v175, s[0:1], 0, v163, s[0:1]
	v_add_f32_e32 v120, v120, v140
	v_add_f32_e32 v121, v121, v141
	v_add_f32_e32 v122, v122, v142
	v_add_f32_e32 v123, v123, v143
	v_add_f32_e32 v84, v84, v136
	v_add_f32_e32 v85, v85, v137
	v_add_f32_e32 v86, v86, v138
	v_add_f32_e32 v87, v87, v139
	v_cvt_pk_f16_f32 v120, v120, v121
	v_cvt_pk_f16_f32 v121, v122, v123
	v_cvt_pk_f16_f32 v122, v84, v85
; __device__ __forceinline__ float sigm(float x) { return __builtin_amdgcn_rcpf(1.0f + __expf(-x)); }
;     __device__ __forceinline__ void operator()(const f32x4 (&acc)[2][2][4][2], const pg8::Unit& u, int wr, int wc, int fr, int fq) const {
;     ...
;                 for (int ai = 0; ai < 2; ++ai)
; #pragma unroll
;                     for (int m = 0; m < 4; ++m) {
;                         f32x4 v = acc[ai][bj][m][n] + bv;
; #pragma unroll
;                         for (int j = 0; j < 4; ++j) { const float sg = sc * sigm(v[j]); v[j] = act ? sg : v[j]; }
;                         u32x2 w; w.x = pk_f16(v[0], v[1]); w.y = pk_f16(v[2], v[3]);
;                         *(u32x2*)(base + (size_t)(ai * 128 + m * 16) * RW + bj * 128 + 4 * n) = w;
;                     }
	v_cvt_pk_f16_f32 v123, v86, v87
	global_store_dwordx4 v[174:175], v[120:123], off
	v_add_f32_e32 v52, v52, v132
	v_add_f32_e32 v53, v53, v133
	v_add_f32_e32 v54, v54, v134
	v_add_f32_e32 v55, v55, v135
	v_add_f32_e32 v20, v20, v96
	v_add_f32_e32 v21, v21, v97
	v_add_f32_e32 v22, v22, v98
	v_add_f32_e32 v23, v23, v99
	v_cvt_pk_f16_f32 v52, v52, v53
	v_cvt_pk_f16_f32 v53, v54, v55
	v_cvt_pk_f16_f32 v54, v20, v21
	v_cvt_pk_f16_f32 v55, v22, v23
	global_store_dwordx4 v[174:175], v[52:55], off offset:256
	s_mov_b32 s0, 0x18000
	v_add_co_u32_e64 v172, s[0:1], s0, v162
	v_addc_co_u32_e64 v173, s[0:1], 0, v163, s[0:1]
	v_add_f32_e32 v116, v116, v140
	v_add_f32_e32 v117, v117, v141
	v_add_f32_e32 v118, v118, v142
	v_add_f32_e32 v119, v119, v143
	v_add_f32_e32 v80, v80, v136
	v_add_f32_e32 v81, v81, v137
	v_add_f32_e32 v82, v82, v138
	v_add_f32_e32 v83, v83, v139
	v_cvt_pk_f16_f32 v116, v116, v117
	v_cvt_pk_f16_f32 v117, v118, v119
	v_cvt_pk_f16_f32 v118, v80, v81
	v_cvt_pk_f16_f32 v119, v82, v83
	global_store_dwordx4 v[172:173], v[116:119], off
	v_add_f32_e32 v48, v48, v132
	v_add_f32_e32 v49, v49, v133
	v_add_f32_e32 v50, v50, v134
	v_add_f32_e32 v51, v51, v135
	v_add_f32_e32 v16, v16, v96
	v_add_f32_e32 v17, v17, v97
	v_add_f32_e32 v18, v18, v98
	v_add_f32_e32 v19, v19, v99
	v_cvt_pk_f16_f32 v48, v48, v49
	v_cvt_pk_f16_f32 v49, v50, v51
	v_cvt_pk_f16_f32 v50, v16, v17
	v_cvt_pk_f16_f32 v51, v18, v19
	global_store_dwordx4 v[172:173], v[48:51], off offset:256
	v_add_co_u32_e64 v174, s[0:1], s85, v162
	v_addc_co_u32_e64 v175, s[0:1], 0, v163, s[0:1]
	v_add_f32_e32 v112, v112, v140
	v_add_f32_e32 v113, v113, v141
	v_add_f32_e32 v114, v114, v142
	v_add_f32_e32 v115, v115, v143
	v_add_f32_e32 v76, v76, v136
	v_add_f32_e32 v77, v77, v137
	v_add_f32_e32 v78, v78, v138
	v_add_f32_e32 v79, v79, v139
	v_cvt_pk_f16_f32 v112, v112, v113
	v_cvt_pk_f16_f32 v113, v114, v115
	v_cvt_pk_f16_f32 v114, v76, v77
	v_cvt_pk_f16_f32 v115, v78, v79
	global_store_dwordx4 v[174:175], v[112:115], off
	v_add_f32_e32 v44, v44, v132
	v_add_f32_e32 v45, v45, v133
	v_add_f32_e32 v46, v46, v134
	v_add_f32_e32 v47, v47, v135
	v_add_f32_e32 v12, v12, v96
	v_add_f32_e32 v13, v13, v97
	v_add_f32_e32 v14, v14, v98
	v_add_f32_e32 v15, v15, v99
	v_cvt_pk_f16_f32 v44, v44, v45
	v_cvt_pk_f16_f32 v45, v46, v47
	v_cvt_pk_f16_f32 v46, v12, v13
	v_cvt_pk_f16_f32 v47, v14, v15
	global_store_dwordx4 v[174:175], v[44:47], off offset:256
	v_add_co_u32_e64 v172, s[0:1], s94, v162
	v_addc_co_u32_e64 v173, s[0:1], 0, v163, s[0:1]
	v_add_f32_e32 v108, v108, v140
	v_add_f32_e32 v109, v109, v141
	v_add_f32_e32 v110, v110, v142
	v_add_f32_e32 v111, v111, v143
	v_add_f32_e32 v72, v72, v136
	v_add_f32_e32 v73, v73, v137
	v_add_f32_e32 v74, v74, v138
	v_add_f32_e32 v75, v75, v139
	v_cvt_pk_f16_f32 v108, v108, v109
	v_cvt_pk_f16_f32 v109, v110, v111
	v_cvt_pk_f16_f32 v110, v72, v73
	v_cvt_pk_f16_f32 v111, v74, v75
	global_store_dwordx4 v[172:173], v[108:111], off
	v_add_f32_e32 v40, v40, v132
	v_add_f32_e32 v41, v41, v133
	v_add_f32_e32 v42, v42, v134
	v_add_f32_e32 v43, v43, v135
	v_add_f32_e32 v8, v8, v96
	v_add_f32_e32 v9, v9, v97
	v_add_f32_e32 v10, v10, v98
	v_add_f32_e32 v11, v11, v99
	v_cvt_pk_f16_f32 v40, v40, v41
	v_cvt_pk_f16_f32 v41, v42, v43
	v_cvt_pk_f16_f32 v42, v8, v9
	v_cvt_pk_f16_f32 v43, v10, v11
	global_store_dwordx4 v[172:173], v[40:43], off offset:256
	v_add_co_u32_e64 v174, s[0:1], s95, v162
	v_addc_co_u32_e64 v175, s[0:1], 0, v163, s[0:1]
	v_add_f32_e32 v104, v104, v140
	v_add_f32_e32 v105, v105, v141
	v_add_f32_e32 v106, v106, v142
	v_add_f32_e32 v107, v107, v143
	v_add_f32_e32 v68, v68, v136
	v_add_f32_e32 v69, v69, v137
	v_add_f32_e32 v70, v70, v138
	v_add_f32_e32 v71, v71, v139
	v_cvt_pk_f16_f32 v104, v104, v105
	v_cvt_pk_f16_f32 v105, v106, v107
	v_cvt_pk_f16_f32 v106, v68, v69
	v_cvt_pk_f16_f32 v107, v70, v71
	global_store_dwordx4 v[174:175], v[104:107], off
	v_add_f32_e32 v36, v36, v132
	v_add_f32_e32 v37, v37, v133
	v_add_f32_e32 v38, v38, v134
	v_add_f32_e32 v39, v39, v135
	v_add_f32_e32 v4, v4, v96
	v_add_f32_e32 v5, v5, v97
	v_add_f32_e32 v6, v6, v98
	v_add_f32_e32 v7, v7, v99
	v_cvt_pk_f16_f32 v36, v36, v37
	v_cvt_pk_f16_f32 v37, v38, v39
	v_cvt_pk_f16_f32 v38, v4, v5
	v_cvt_pk_f16_f32 v39, v6, v7
	global_store_dwordx4 v[174:175], v[36:39], off offset:256
	v_add_co_u32_e64 v172, s[0:1], s96, v162
	v_addc_co_u32_e64 v173, s[0:1], 0, v163, s[0:1]
	v_add_f32_e32 v100, v100, v140
	v_add_f32_e32 v101, v101, v141
	v_add_f32_e32 v102, v102, v142
	v_add_f32_e32 v103, v103, v143
	v_add_f32_e32 v64, v64, v136
	v_add_f32_e32 v65, v65, v137
	v_add_f32_e32 v66, v66, v138
	v_add_f32_e32 v67, v67, v139
	v_cvt_pk_f16_f32 v100, v100, v101
	v_cvt_pk_f16_f32 v101, v102, v103
	v_cvt_pk_f16_f32 v102, v64, v65
	v_cvt_pk_f16_f32 v103, v66, v67
	global_store_dwordx4 v[172:173], v[100:103], off
	v_add_f32_e32 v32, v32, v132
	v_add_f32_e32 v33, v33, v133
	v_add_f32_e32 v34, v34, v134
	v_add_f32_e32 v35, v35, v135
	v_add_f32_e32 v0, v0, v96
	v_add_f32_e32 v1, v1, v97
	v_add_f32_e32 v2, v2, v98
	v_add_f32_e32 v3, v3, v99
	v_cvt_pk_f16_f32 v32, v32, v33
	v_cvt_pk_f16_f32 v33, v34, v35
	v_cvt_pk_f16_f32 v34, v0, v1
	v_cvt_pk_f16_f32 v35, v2, v3
	global_store_dwordx4 v[172:173], v[32:35], off offset:256
.Lp8_epi_done:
	s_and_b64 vcc, exec, s[2:3]
	s_cbranch_vccnz .LBB0_704
